# GEMM tile setup: redundant 127-instruction accumulator zeroing block moved off the hot path into a cold stub (loop placement kept mod 128)
# speedup vs baseline: 1.0077x; 1.0024x over previous
.Lgemm_zero_stub:
	v_mov_b32_e32 v118, v119
	v_mov_b32_e32 v117, v119
	v_mov_b32_e32 v116, v119
	v_mov_b32_e32 v127, v119
	v_mov_b32_e32 v126, v119
	v_mov_b32_e32 v125, v119
	v_mov_b32_e32 v124, v119
	v_mov_b32_e32 v123, v119
	v_mov_b32_e32 v122, v119
	v_mov_b32_e32 v121, v119
	v_mov_b32_e32 v120, v119
	v_mov_b32_e32 v115, v119
	v_mov_b32_e32 v114, v119
	v_mov_b32_e32 v113, v119
	v_mov_b32_e32 v112, v119
	v_mov_b32_e32 v111, v119
	v_mov_b32_e32 v110, v119
	v_mov_b32_e32 v109, v119
	v_mov_b32_e32 v108, v119
	v_mov_b32_e32 v107, v119
	v_mov_b32_e32 v106, v119
	v_mov_b32_e32 v105, v119
	v_mov_b32_e32 v104, v119
	v_mov_b32_e32 v103, v119
	v_mov_b32_e32 v102, v119
	v_mov_b32_e32 v101, v119
	v_mov_b32_e32 v100, v119
	v_mov_b32_e32 v99, v119
	v_mov_b32_e32 v98, v119
	v_mov_b32_e32 v97, v119
	v_mov_b32_e32 v96, v119
	v_mov_b32_e32 v95, v119
	v_mov_b32_e32 v94, v119
	v_mov_b32_e32 v93, v119
	v_mov_b32_e32 v92, v119
	v_mov_b32_e32 v91, v119
	v_mov_b32_e32 v90, v119
	v_mov_b32_e32 v89, v119
	v_mov_b32_e32 v88, v119
	v_mov_b32_e32 v87, v119
	v_mov_b32_e32 v86, v119
	v_mov_b32_e32 v85, v119
	v_mov_b32_e32 v84, v119
	v_mov_b32_e32 v83, v119
	v_mov_b32_e32 v82, v119
	v_mov_b32_e32 v81, v119
	v_mov_b32_e32 v80, v119
	v_mov_b32_e32 v79, v119
	v_mov_b32_e32 v78, v119
	v_mov_b32_e32 v77, v119
	v_mov_b32_e32 v76, v119
	v_mov_b32_e32 v75, v119
	v_mov_b32_e32 v74, v119
	v_mov_b32_e32 v73, v119
	v_mov_b32_e32 v72, v119
	v_mov_b32_e32 v71, v119
	v_mov_b32_e32 v70, v119
	v_mov_b32_e32 v69, v119
	v_mov_b32_e32 v68, v119
	v_mov_b32_e32 v67, v119
	v_mov_b32_e32 v66, v119
	v_mov_b32_e32 v65, v119
	v_mov_b32_e32 v64, v119
	v_mov_b32_e32 v63, v119
	v_mov_b32_e32 v62, v119
	v_mov_b32_e32 v61, v119
	v_mov_b32_e32 v60, v119
	v_mov_b32_e32 v59, v119
	v_mov_b32_e32 v58, v119
	v_mov_b32_e32 v57, v119
	v_mov_b32_e32 v56, v119
	v_mov_b32_e32 v55, v119
	v_mov_b32_e32 v54, v119
	v_mov_b32_e32 v53, v119
	v_mov_b32_e32 v52, v119
	v_mov_b32_e32 v51, v119
	v_mov_b32_e32 v50, v119
	v_mov_b32_e32 v49, v119
	v_mov_b32_e32 v48, v119
	v_mov_b32_e32 v47, v119
	v_mov_b32_e32 v46, v119
	v_mov_b32_e32 v45, v119
	v_mov_b32_e32 v44, v119
	v_mov_b32_e32 v43, v119
	v_mov_b32_e32 v42, v119
	v_mov_b32_e32 v41, v119
	v_mov_b32_e32 v40, v119
	v_mov_b32_e32 v39, v119
	v_mov_b32_e32 v38, v119
	v_mov_b32_e32 v37, v119
	v_mov_b32_e32 v36, v119
	v_mov_b32_e32 v35, v119
	v_mov_b32_e32 v34, v119
	v_mov_b32_e32 v33, v119
	v_mov_b32_e32 v32, v119
	v_mov_b32_e32 v31, v119
	v_mov_b32_e32 v30, v119
	v_mov_b32_e32 v29, v119
	v_mov_b32_e32 v28, v119
	v_mov_b32_e32 v27, v119
	v_mov_b32_e32 v26, v119
	v_mov_b32_e32 v25, v119
	v_mov_b32_e32 v24, v119
	v_mov_b32_e32 v23, v119
	v_mov_b32_e32 v22, v119
	v_mov_b32_e32 v21, v119
	v_mov_b32_e32 v20, v119
	v_mov_b32_e32 v19, v119
	v_mov_b32_e32 v18, v119
	v_mov_b32_e32 v17, v119
	v_mov_b32_e32 v16, v119
	v_mov_b32_e32 v15, v119
	v_mov_b32_e32 v14, v119
	v_mov_b32_e32 v13, v119
	v_mov_b32_e32 v12, v119
	v_mov_b32_e32 v11, v119
	v_mov_b32_e32 v10, v119
	v_mov_b32_e32 v9, v119
	v_mov_b32_e32 v8, v119
	v_mov_b32_e32 v7, v119
	v_mov_b32_e32 v6, v119
	v_mov_b32_e32 v5, v119
	v_mov_b32_e32 v4, v119
	v_mov_b32_e32 v3, v119
	v_mov_b32_e32 v2, v119
	v_mov_b32_e32 v1, v119
	v_mov_b32_e32 v0, v119
	s_branch .LBB0_236
	s_nop 0
	s_nop 0
	s_nop 0
	s_nop 0
	s_nop 0
	s_nop 0
	s_nop 0
	s_nop 0
	s_nop 0
	s_nop 0
	s_nop 0
	s_nop 0
	s_nop 0
	s_nop 0
	s_nop 0
	s_nop 0
	s_nop 0
	s_nop 0
	s_nop 0
	s_nop 0
	s_nop 0
	s_nop 0
	s_nop 0
	s_nop 0
	s_nop 0
	s_nop 0
	s_nop 0
	s_nop 0
	s_nop 0
	s_nop 0
	s_nop 0

.LBB0_232:
	v_mov_b32_e32 v119, 0
	v_bitop3_b32 v128, v0, v2, v1 bitop3:0x36
	s_andn2_b64 vcc, exec, s[58:59]
	s_cbranch_vccnz .Lgemm_zero_stub
	s_mov_b32 s12, s2
	v_readlane_b32 s2, v250, 41
	v_readlane_b32 s3, v250, 42
	v_readlane_b32 s3, v252, 50
	s_mov_b32 s3, 0x10000
	s_addk_i32 s3, 0x100
	v_add_u32_e32 v1, s3, v128
	s_mov_b32 s3, 0x14000
	s_addk_i32 s3, 0x100
	v_add_u32_e32 v2, s3, v128
	s_mov_b32 s3, 0x18000
	s_addk_i32 s3, 0x100
	v_readlane_b32 s52, v250, 19
	v_add_u32_e32 v3, s3, v128
	s_mov_b32 s3, 0x1c000
	v_readlane_b32 s53, v250, 20
	s_ashr_i32 s15, s14, 31
	s_addk_i32 s3, 0x100
	s_lshl_b32 s52, s57, 13
	s_ashr_i32 s43, s42, 31
	s_ashr_i32 s35, s34, 31
	s_ashr_i32 s41, s40, 31
	v_add_u32_e32 v4, s3, v128
	s_or_b32 s79, s17, 0x400
	s_or_b32 s3, s17, 0x800
	s_or_b32 s48, s17, 0xc00
	s_or_b32 s53, s52, 0x400
	s_or_b32 s60, s52, 0x800
	s_or_b32 s61, s52, 0xc00
	s_or_b32 s62, s52, 0x1000
	s_or_b32 s63, s52, 0x1400
	s_or_b32 s90, s52, 0x1800
	s_or_b32 s91, s52, 0x1c00
	s_lshl_b64 s[58:59], s[14:15], 1
	s_add_u32 s15, s58, 0x80
	s_addc_u32 s57, s59, 0
	s_mul_i32 s57, s18, s57
	s_mul_hi_u32 s58, s18, s15
	s_add_i32 s57, s58, s57
	s_mul_i32 s58, s19, s15
	s_add_i32 s57, s57, s58
	s_mul_i32 s15, s18, s15
	v_readlane_b32 s72, v250, 45
	s_mov_b32 s11, s74
	s_mov_b32 s74, s73
	s_add_u32 vcc_lo, s72, s15
	v_readlane_b32 s73, v250, 46
	s_addc_u32 vcc_hi, s73, s57
	s_lshl_b64 s[58:59], s[42:43], 1
	s_add_u32 s15, s58, 0x80
	s_addc_u32 s43, s59, 0
	s_mul_i32 s43, s18, s43
	s_mul_hi_u32 s57, s18, s15
	s_add_i32 s43, s57, s43
	s_mul_i32 s57, s19, s15
	s_add_i32 s43, s43, s57
	s_mul_i32 s15, s18, s15
	v_readlane_b32 s58, v250, 43
	s_add_u32 s64, s58, s15
	v_readlane_b32 s57, v250, 44
	s_addc_u32 s65, s57, s43
	s_lshl_b64 s[34:35], s[34:35], 1
	s_add_u32 s15, s34, 0x80
	s_addc_u32 s34, s35, 0
	s_mul_i32 s34, s18, s34
	s_mul_hi_u32 s35, s18, s15
	s_add_i32 s34, s35, s34
	s_mul_i32 s35, s19, s15
	s_add_i32 s35, s34, s35
	s_mul_i32 s15, s18, s15
	s_add_u32 s34, s72, s15
	s_addc_u32 s35, s73, s35
	s_lshl_b64 s[40:41], s[40:41], 1
	s_add_u32 s15, s40, 0x80
	s_addc_u32 s40, s41, 0
	s_mul_i32 s40, s18, s40
	s_mul_hi_u32 s41, s18, s15
	s_add_i32 s40, s41, s40
	s_mul_i32 s41, s19, s15
	s_add_i32 s40, s40, s41
	s_mul_i32 s15, s18, s15
	v_add_u32_e32 v130, 0x100, v129
	s_add_u32 s58, s58, s15
	v_mov_b32_e32 v0, 0
	s_mov_b32 s8, s88
	s_mov_b32 s2, s31
	s_mov_b32 s9, s30
	s_mov_b32 s88, s20
	s_addc_u32 s59, s57, s40
	s_mov_b32 s15, 0
	v_add_u32_e32 v131, s17, v1
	v_add_u32_e32 v132, s60, v130
	v_add_u32_e32 v133, s62, v130
	v_add_u32_e32 v134, s90, v130
	v_add_u32_e32 v135, s17, v2
	v_add_u32_e32 v136, s17, v3
	v_add_u32_e32 v137, s17, v4
	s_mov_b64 s[40:41], s[68:69]
	v_mov_b32_e32 v1, v0
	v_mov_b32_e32 v2, v0
	v_mov_b32_e32 v3, v0
	v_mov_b32_e32 v4, v0
	v_mov_b32_e32 v5, v0
	v_mov_b32_e32 v6, v0
	v_mov_b32_e32 v7, v0
	v_mov_b32_e32 v8, v0
	v_mov_b32_e32 v9, v0
	v_mov_b32_e32 v10, v0
	v_mov_b32_e32 v11, v0
	v_mov_b32_e32 v12, v0
	v_mov_b32_e32 v13, v0
	v_mov_b32_e32 v14, v0
	v_mov_b32_e32 v15, v0
	v_mov_b32_e32 v16, v0
	v_mov_b32_e32 v17, v0
	v_mov_b32_e32 v18, v0
	v_mov_b32_e32 v19, v0
	v_mov_b32_e32 v20, v0
	v_mov_b32_e32 v21, v0
	v_mov_b32_e32 v22, v0
	v_mov_b32_e32 v23, v0
	v_mov_b32_e32 v24, v0
	v_mov_b32_e32 v25, v0
	v_mov_b32_e32 v26, v0
	v_mov_b32_e32 v27, v0
	v_mov_b32_e32 v28, v0
	v_mov_b32_e32 v29, v0
	v_mov_b32_e32 v30, v0
	v_mov_b32_e32 v31, v0
	v_mov_b32_e32 v32, v0
	v_mov_b32_e32 v33, v0
	v_mov_b32_e32 v34, v0
	v_mov_b32_e32 v35, v0
	v_mov_b32_e32 v36, v0
	v_mov_b32_e32 v37, v0
	v_mov_b32_e32 v38, v0
	v_mov_b32_e32 v39, v0
	v_mov_b32_e32 v40, v0
	v_mov_b32_e32 v41, v0
	v_mov_b32_e32 v42, v0
	v_mov_b32_e32 v43, v0
	v_mov_b32_e32 v44, v0
	v_mov_b32_e32 v45, v0
	v_mov_b32_e32 v46, v0
	v_mov_b32_e32 v47, v0
	v_mov_b32_e32 v48, v0
	v_mov_b32_e32 v49, v0
	v_mov_b32_e32 v50, v0
	v_mov_b32_e32 v51, v0
	v_mov_b32_e32 v52, v0
	v_mov_b32_e32 v53, v0
	v_mov_b32_e32 v54, v0
	v_mov_b32_e32 v55, v0
	v_mov_b32_e32 v56, v0
	v_mov_b32_e32 v57, v0
	v_mov_b32_e32 v58, v0
	v_mov_b32_e32 v59, v0
	v_mov_b32_e32 v60, v0
	v_mov_b32_e32 v61, v0
	v_mov_b32_e32 v62, v0
	v_mov_b32_e32 v63, v0
	v_mov_b32_e32 v64, v0
	v_mov_b32_e32 v65, v0
	v_mov_b32_e32 v66, v0
	v_mov_b32_e32 v67, v0
	v_mov_b32_e32 v68, v0
	v_mov_b32_e32 v69, v0
	v_mov_b32_e32 v70, v0
	v_mov_b32_e32 v71, v0
	v_mov_b32_e32 v72, v0
	v_mov_b32_e32 v73, v0
	v_mov_b32_e32 v74, v0
	v_mov_b32_e32 v75, v0
	v_mov_b32_e32 v76, v0
	v_mov_b32_e32 v77, v0
	v_mov_b32_e32 v78, v0
	v_mov_b32_e32 v79, v0
	v_mov_b32_e32 v80, v0
	v_mov_b32_e32 v81, v0
	v_mov_b32_e32 v82, v0
	v_mov_b32_e32 v83, v0
	v_mov_b32_e32 v84, v0
	v_mov_b32_e32 v85, v0
	v_mov_b32_e32 v86, v0
	v_mov_b32_e32 v87, v0
	v_mov_b32_e32 v88, v0
	v_mov_b32_e32 v89, v0
	v_mov_b32_e32 v90, v0
	v_mov_b32_e32 v91, v0
	v_mov_b32_e32 v92, v0
	v_mov_b32_e32 v93, v0
	v_mov_b32_e32 v94, v0
	v_mov_b32_e32 v95, v0
	v_mov_b32_e32 v96, v0
	v_mov_b32_e32 v97, v0
	v_mov_b32_e32 v98, v0
	v_mov_b32_e32 v99, v0
	v_mov_b32_e32 v100, v0
	v_mov_b32_e32 v101, v0
	v_mov_b32_e32 v102, v0
	v_mov_b32_e32 v103, v0
	v_mov_b32_e32 v104, v0
	v_mov_b32_e32 v105, v0
	v_mov_b32_e32 v106, v0
	v_mov_b32_e32 v107, v0
	v_mov_b32_e32 v108, v0
	v_mov_b32_e32 v109, v0
	v_mov_b32_e32 v110, v0
	v_mov_b32_e32 v111, v0
	v_mov_b32_e32 v112, v0
	v_mov_b32_e32 v113, v0
	v_mov_b32_e32 v114, v0
	v_mov_b32_e32 v115, v0
	v_mov_b32_e32 v120, v0
	v_mov_b32_e32 v121, v0
	v_mov_b32_e32 v122, v0
	v_mov_b32_e32 v123, v0
	v_mov_b32_e32 v124, v0
	v_mov_b32_e32 v125, v0
	v_mov_b32_e32 v126, v0
	v_mov_b32_e32 v127, v0
	v_mov_b32_e32 v116, v0
	v_mov_b32_e32 v117, v0
	v_mov_b32_e32 v118, v0
	v_mov_b32_e32 v119, v0
	s_mov_b64 s[72:73], 0x80
